# strategy 7.4: one static s_setprio 1 for the younger half (waves 4-7) at kernel start, the per-MMA-block priority flips of the four GEMM loops deleted
# speedup vs baseline: 1.0009x; 1.0009x over previous
.LBB0_7:
	s_or_b64 exec, exec, s[0:1]
	s_add_u32 s0, s70, 0x10000
	s_addc_u32 s1, s71, 0
	v_writelane_b32 v249, s0, 33
	v_and_b32_e32 v1, 63, v0
	s_nop 0
	v_writelane_b32 v249, s1, 34
	s_add_u32 s0, s70, 0x1d000000
	s_addc_u32 s1, s71, 0
	v_writelane_b32 v249, s0, 35
	s_nop 1
	v_writelane_b32 v249, s1, 36
	s_add_u32 s0, s70, 0x100000
	s_addc_u32 s1, s71, 0
	v_writelane_b32 v249, s0, 37
	s_nop 1
	v_writelane_b32 v249, s1, 38
	s_add_u32 s0, s70, 0x1900000
	s_addc_u32 s1, s71, 0
	v_writelane_b32 v249, s0, 39
	s_nop 1
	v_writelane_b32 v249, s1, 40
	s_add_u32 s0, s70, 0x22300000
	s_addc_u32 s1, s71, 0
	v_writelane_b32 v249, s0, 41
	s_nop 1
	v_writelane_b32 v249, s1, 42
	s_add_u32 s0, s70, 0x2400000
	s_addc_u32 s1, s71, 0
	v_writelane_b32 v249, s0, 43
	s_nop 1
	v_writelane_b32 v249, s1, 44
	s_add_u32 s0, s70, 0x2100000
	s_addc_u32 s1, s71, 0
	v_writelane_b32 v249, s0, 45
	s_nop 1
	v_writelane_b32 v249, s1, 46
	s_add_u32 s0, s70, 0x2200000
	s_addc_u32 s1, s71, 0
	v_writelane_b32 v249, s0, 47
	s_nop 1
	v_writelane_b32 v249, s1, 48
	s_nop 0
	v_readlane_b32 s0, v249, 4
	s_lshr_b32 s0, s0, 6
	s_nop 0
	v_writelane_b32 v249, s0, 49
	s_cmp_ge_u32 s0, 4
	s_cbranch_scc0 .Lprio_done
	s_setprio 1
.Lprio_done:
	s_nop 0
	v_readlane_b32 s0, v249, 7
	s_and_b32 s1, s0, 7
	v_writelane_b32 v249, s1, 50
	s_ashr_i32 s0, s0, 3
	v_writelane_b32 v249, s0, 51
	s_nop 0
	v_readlane_b32 s0, v249, 8
	v_readlane_b32 s1, v249, 9
	s_mov_b64 s[4:5], s[0:1]
	s_cmp_lt_i32 s4, 1
	v_readlane_b32 s2, v249, 10
	v_readlane_b32 s3, v249, 11
	s_cselect_b64 s[0:1], -1, 0
	s_cmp_gt_i32 s5, 0
	s_cselect_b64 s[2:3], -1, 0
	s_and_b64 s[0:1], s[0:1], s[2:3]
	s_andn2_b64 vcc, exec, s[0:1]
	s_cbranch_vccnz .LBB0_455
	s_cmpk_gt_i32 s8, 0xbf
	s_mov_b32 s9, 0
	s_cbranch_scc1 .LBB0_13
	v_and_b32_e32 v3, 0x100, v0
	v_mov_b32_e32 v4, 2
	v_readlane_b32 s1, v249, 49
	v_lshlrev_b32_e32 v3, 2, v3
	v_lshlrev_b32_sdwa v4, v4, v0 dst_sel:DWORD dst_unused:UNUSED_PAD src0_sel:DWORD src1_sel:BYTE_0
	s_lshl_b32 s0, s1, 11
	v_add3_u32 v26, 0, v3, v4
	v_lshrrev_b32_e32 v3, 8, v0
	s_add_i32 s2, s0, 0
	s_lshl_b32 s10, s1, 5
	v_mul_u32_u24_e32 v3, 0x1800, v3
	v_readlane_b32 s0, v249, 33
	v_lshlrev_b32_e32 v14, 2, v3
	v_mov_b32_e32 v15, 0
	v_readlane_b32 s1, v249, 34
	v_readlane_b32 s12, v249, 12
	v_lshlrev_b32_e32 v2, 4, v1
	v_lshl_add_u64 v[6:7], s[0:1], 0, v[14:15]
	v_mov_b32_e32 v5, v15
	v_mov_b32_e32 v3, v15
	v_readlane_b32 s18, v249, 18
	v_readlane_b32 s19, v249, 19
	v_lshl_add_u64 v[16:17], v[6:7], 0, v[4:5]
	v_readlane_b32 s13, v249, 13
	v_readlane_b32 s14, v249, 14
	v_readlane_b32 s15, v249, 15
	v_readlane_b32 s16, v249, 16
	v_readlane_b32 s17, v249, 17
	v_lshl_add_u64 v[4:5], s[18:19], 0, v[2:3]
	s_mov_b64 s[0:1], 0x18000
	v_lshl_add_u64 v[18:19], v[4:5], 0, s[0:1]
	s_movk_i32 s11, 0x6000
	v_mov_b32_e32 v14, 0x2000
	s_mov_b32 s12, 0xfffe8000
	s_mov_b32 s13, 0xfffee000
	s_mov_b32 s14, 0xffff4000
	s_movk_i32 s15, 0xa000
	s_mov_b32 s16, 0xc000
	s_mov_b32 s17, 0x12000
	s_mov_b64 s[0:1], 0x30000
	v_add_u32_e32 v27, s2, v2
	s_mov_b32 s18, s8
	v_readlane_b32 s20, v249, 20
	v_readlane_b32 s21, v249, 21
	v_readlane_b32 s22, v249, 22
	v_readlane_b32 s23, v249, 23
	v_readlane_b32 s24, v249, 24
	v_readlane_b32 s25, v249, 25
	v_readlane_b32 s26, v249, 26
	v_readlane_b32 s27, v249, 27

.LBB0_257:
	s_or_b64 exec, exec, s[42:43]
	s_lshl_b32 s2, s80, 7
	v_lshl_add_u64 v[156:157], v[90:91], 0, s[2:3]
	s_mov_b64 s[42:43], 0x100
	v_lshl_add_u64 v[94:95], v[156:157], 0, s[42:43]
	v_add_u32_e32 v167, s74, v162
	v_cndmask_b32_e64 v225, v151, v95, s[6:7]
	v_cndmask_b32_e64 v224, v150, v94, s[6:7]
	ds_read_b128 v[94:97], v167
	ds_read_b128 v[152:155], v167 offset:1024
	ds_read_b128 v[168:171], v167 offset:2048
	ds_read_b128 v[172:175], v167 offset:3072
	v_add_u32_e32 v167, s75, v162
	ds_read_b128 v[176:179], v167
	ds_read_b128 v[180:183], v167 offset:1024
	ds_read_b128 v[184:187], v167 offset:2048
	ds_read_b128 v[188:191], v167 offset:3072
	s_add_u32 s2, s8, s2
	s_addc_u32 s42, s9, 0
	s_add_u32 s2, s2, 0x100
	s_addc_u32 s42, s42, 0
	s_and_b64 s[6:7], s[6:7], exec
	s_cselect_b32 s7, s42, s29
	s_cselect_b32 s6, s2, s31
	s_mov_b64 s[42:43], 0x80080
	v_lshl_add_u64 v[156:157], v[156:157], 0, s[42:43]
	v_lshl_add_u64 v[226:227], v[156:157], 0, v[138:139]
	s_add_i32 m0, s15, 0xc000
	ds_read_b128 v[192:195], v164
	ds_read_b128 v[196:199], v164 offset:1024
	ds_read_b128 v[200:203], v164 offset:2048
	ds_read_b128 v[204:207], v164 offset:3072
	ds_read_b128 v[208:211], v164 offset:4096
	ds_read_b128 v[212:215], v164 offset:5120
	ds_read_b128 v[216:219], v164 offset:6144
	ds_read_b128 v[220:223], v164 offset:7168
	global_load_lds_dwordx4 v[226:227], off
	v_lshl_add_u64 v[156:157], v[156:157], 0, v[142:143]
	s_add_i32 m0, s15, 0xe000
	s_nop 0
	global_load_lds_dwordx4 v[156:157], off
	s_waitcnt vmcnt(8)
	s_waitcnt lgkmcnt(0)
	s_barrier
	s_waitcnt lgkmcnt(0)
	v_mfma_f32_16x16x32_bf16 v[70:73], v[94:97], v[192:195], v[70:73]
	v_mfma_f32_16x16x32_bf16 v[66:69], v[168:171], v[192:195], v[66:69]
	v_mfma_f32_16x16x32_bf16 v[62:65], v[94:97], v[200:203], v[62:65]
	v_mfma_f32_16x16x32_bf16 v[58:61], v[168:171], v[200:203], v[58:61]
	v_mfma_f32_16x16x32_bf16 v[54:57], v[94:97], v[208:211], v[54:57]
	v_mfma_f32_16x16x32_bf16 v[50:53], v[168:171], v[208:211], v[50:53]
	v_mfma_f32_16x16x32_bf16 v[46:49], v[94:97], v[216:219], v[46:49]
	v_mfma_f32_16x16x32_bf16 v[42:45], v[168:171], v[216:219], v[42:45]
	v_mfma_f32_16x16x32_bf16 v[70:73], v[152:155], v[196:199], v[70:73]
	v_mfma_f32_16x16x32_bf16 v[66:69], v[172:175], v[196:199], v[66:69]
	v_mfma_f32_16x16x32_bf16 v[62:65], v[152:155], v[204:207], v[62:65]
	v_mfma_f32_16x16x32_bf16 v[58:61], v[172:175], v[204:207], v[58:61]
	v_mfma_f32_16x16x32_bf16 v[54:57], v[152:155], v[212:215], v[54:57]
	v_mfma_f32_16x16x32_bf16 v[50:53], v[172:175], v[212:215], v[50:53]
	v_mfma_f32_16x16x32_bf16 v[46:49], v[152:155], v[220:223], v[46:49]
	v_mfma_f32_16x16x32_bf16 v[42:45], v[172:175], v[220:223], v[42:45]
	v_mfma_f32_16x16x32_bf16 v[134:137], v[176:179], v[192:195], v[134:137]
	v_mfma_f32_16x16x32_bf16 v[130:133], v[184:187], v[192:195], v[130:133]
	v_mfma_f32_16x16x32_bf16 v[126:129], v[176:179], v[200:203], v[126:129]
	v_mfma_f32_16x16x32_bf16 v[122:125], v[184:187], v[200:203], v[122:125]
	v_mfma_f32_16x16x32_bf16 v[118:121], v[176:179], v[208:211], v[118:121]
	v_mfma_f32_16x16x32_bf16 v[114:117], v[184:187], v[208:211], v[114:117]
	v_mfma_f32_16x16x32_bf16 v[110:113], v[176:179], v[216:219], v[110:113]
	v_mfma_f32_16x16x32_bf16 v[106:109], v[184:187], v[216:219], v[106:109]
	v_mfma_f32_16x16x32_bf16 v[134:137], v[180:183], v[196:199], v[134:137]
	v_mfma_f32_16x16x32_bf16 v[130:133], v[188:191], v[196:199], v[130:133]
	v_mfma_f32_16x16x32_bf16 v[126:129], v[180:183], v[204:207], v[126:129]
	v_mfma_f32_16x16x32_bf16 v[122:125], v[188:191], v[204:207], v[122:125]
	v_mfma_f32_16x16x32_bf16 v[118:121], v[180:183], v[212:215], v[118:121]
	v_mfma_f32_16x16x32_bf16 v[114:117], v[188:191], v[212:215], v[114:117]
	v_mfma_f32_16x16x32_bf16 v[110:113], v[180:183], v[220:223], v[110:113]
	v_mfma_f32_16x16x32_bf16 v[106:109], v[188:191], v[220:223], v[106:109]
	s_barrier
	s_add_i32 s2, s74, s48
	v_lshl_add_u64 v[156:157], s[6:7], 0, v[140:141]
	s_mov_b32 m0, s2
	ds_read_b128 v[192:195], v164 offset:16384
	ds_read_b128 v[196:199], v164 offset:17408
	ds_read_b128 v[200:203], v164 offset:18432
	ds_read_b128 v[204:207], v164 offset:19456
	ds_read_b128 v[208:211], v164 offset:20480
	ds_read_b128 v[212:215], v164 offset:21504
	ds_read_b128 v[216:219], v164 offset:22528
	ds_read_b128 v[220:223], v164 offset:23552
	global_load_lds_dwordx4 v[156:157], off
	s_add_i32 m0, s2, 0x2000
	s_add_u32 s42, s6, 0x80000
	v_lshl_add_u64 v[226:227], s[6:7], 0, v[144:145]
	s_addc_u32 s43, s7, 0
	s_add_i32 s2, s75, s48
	global_load_lds_dwordx4 v[226:227], off
	v_lshl_add_u64 v[228:229], s[42:43], 0, v[140:141]
	s_mov_b32 m0, s2
	v_lshl_add_u64 v[230:231], v[224:225], 0, v[142:143]
	global_load_lds_dwordx4 v[228:229], off
	v_lshl_add_u64 v[228:229], s[42:43], 0, v[144:145]
	s_add_i32 m0, s2, 0x2000
	s_nop 0
	global_load_lds_dwordx4 v[228:229], off
	v_lshl_add_u64 v[228:229], v[224:225], 0, v[138:139]
	s_mov_b32 m0, s15
	s_nop 0
	global_load_lds_dwordx4 v[228:229], off
	s_mov_b32 m0, s17
	s_nop 0
	global_load_lds_dwordx4 v[230:231], off
	s_waitcnt vmcnt(8)
	s_waitcnt lgkmcnt(0)
	s_barrier
	s_waitcnt lgkmcnt(0)
	v_mfma_f32_16x16x32_bf16 v[34:37], v[94:97], v[192:195], v[34:37]
	v_mfma_f32_16x16x32_bf16 v[26:29], v[168:171], v[192:195], v[26:29]
	v_mfma_f32_16x16x32_bf16 v[22:25], v[94:97], v[200:203], v[22:25]
	v_mfma_f32_16x16x32_bf16 v[18:21], v[168:171], v[200:203], v[18:21]
	v_mfma_f32_16x16x32_bf16 v[14:17], v[94:97], v[208:211], v[14:17]
	v_mfma_f32_16x16x32_bf16 v[10:13], v[168:171], v[208:211], v[10:13]
	v_mfma_f32_16x16x32_bf16 v[6:9], v[94:97], v[216:219], v[6:9]
	v_mfma_f32_16x16x32_bf16 v[2:5], v[168:171], v[216:219], v[2:5]
	v_mfma_f32_16x16x32_bf16 v[34:37], v[152:155], v[196:199], v[34:37]
	v_mfma_f32_16x16x32_bf16 v[26:29], v[172:175], v[196:199], v[26:29]
	v_mfma_f32_16x16x32_bf16 v[22:25], v[152:155], v[204:207], v[22:25]
	v_mfma_f32_16x16x32_bf16 v[18:21], v[172:175], v[204:207], v[18:21]
	v_mfma_f32_16x16x32_bf16 v[14:17], v[152:155], v[212:215], v[14:17]
	v_mfma_f32_16x16x32_bf16 v[10:13], v[172:175], v[212:215], v[10:13]
	v_mfma_f32_16x16x32_bf16 v[6:9], v[152:155], v[220:223], v[6:9]
	v_mfma_f32_16x16x32_bf16 v[2:5], v[172:175], v[220:223], v[2:5]
	v_mfma_f32_16x16x32_bf16 v[98:101], v[184:187], v[192:195], v[98:101]
	v_mfma_f32_16x16x32_bf16 v[86:89], v[176:179], v[200:203], v[86:89]
	v_mfma_f32_16x16x32_bf16 v[82:85], v[184:187], v[200:203], v[82:85]
	v_mfma_f32_16x16x32_bf16 v[78:81], v[176:179], v[208:211], v[78:81]
	v_mfma_f32_16x16x32_bf16 v[74:77], v[184:187], v[208:211], v[74:77]
	v_mfma_f32_16x16x32_bf16 v[38:41], v[176:179], v[216:219], v[38:41]
	v_mfma_f32_16x16x32_bf16 v[30:33], v[184:187], v[216:219], v[30:33]
	v_mfma_f32_16x16x32_bf16 v[94:97], v[176:179], v[192:195], v[102:105]
	v_mfma_f32_16x16x32_bf16 v[98:101], v[188:191], v[196:199], v[98:101]
	v_mfma_f32_16x16x32_bf16 v[86:89], v[180:183], v[204:207], v[86:89]
	v_mfma_f32_16x16x32_bf16 v[82:85], v[188:191], v[204:207], v[82:85]
	v_mfma_f32_16x16x32_bf16 v[78:81], v[180:183], v[212:215], v[78:81]
	v_mfma_f32_16x16x32_bf16 v[74:77], v[188:191], v[212:215], v[74:77]
	v_mfma_f32_16x16x32_bf16 v[38:41], v[180:183], v[220:223], v[38:41]
	v_mfma_f32_16x16x32_bf16 v[30:33], v[188:191], v[220:223], v[30:33]
	v_mfma_f32_16x16x32_bf16 v[94:97], v[180:183], v[196:199], v[94:97]
	s_barrier
	s_add_i32 s2, 0, 0x18000
	v_add_u32_e32 v167, s2, v162
	s_add_i32 s44, 0, 0x1c000
	ds_read_b128 v[102:105], v167
	ds_read_b128 v[152:155], v167 offset:1024
	ds_read_b128 v[168:171], v167 offset:2048
	ds_read_b128 v[172:175], v167 offset:3072
	v_add_u32_e32 v167, s44, v162
	ds_read_b128 v[176:179], v167
	ds_read_b128 v[180:183], v167 offset:1024
	ds_read_b128 v[184:187], v167 offset:2048
	ds_read_b128 v[188:191], v167 offset:3072
	s_mov_b64 s[42:43], 0x80000
	v_lshl_add_u64 v[224:225], v[224:225], 0, s[42:43]
	s_mov_b32 m0, s49
	v_lshl_add_u64 v[232:233], v[224:225], 0, v[138:139]
	ds_read_b128 v[192:195], v164 offset:32768
	ds_read_b128 v[196:199], v164 offset:33792
	ds_read_b128 v[200:203], v164 offset:34816
	ds_read_b128 v[204:207], v164 offset:35840
	ds_read_b128 v[208:211], v164 offset:36864
	ds_read_b128 v[212:215], v164 offset:37888
	ds_read_b128 v[216:219], v164 offset:38912
	ds_read_b128 v[220:223], v164 offset:39936
	global_load_lds_dwordx4 v[232:233], off
	v_lshl_add_u64 v[224:225], v[224:225], 0, v[142:143]
	s_mov_b32 m0, s50
	s_nop 0
	global_load_lds_dwordx4 v[224:225], off
	s_waitcnt vmcnt(8)
	s_waitcnt lgkmcnt(0)
	s_barrier
	s_waitcnt lgkmcnt(0)
	v_mfma_f32_16x16x32_bf16 v[70:73], v[102:105], v[192:195], v[70:73]
	v_mfma_f32_16x16x32_bf16 v[66:69], v[168:171], v[192:195], v[66:69]
	v_mfma_f32_16x16x32_bf16 v[62:65], v[102:105], v[200:203], v[62:65]
	v_mfma_f32_16x16x32_bf16 v[58:61], v[168:171], v[200:203], v[58:61]
	v_mfma_f32_16x16x32_bf16 v[54:57], v[102:105], v[208:211], v[54:57]
	v_mfma_f32_16x16x32_bf16 v[50:53], v[168:171], v[208:211], v[50:53]
	v_mfma_f32_16x16x32_bf16 v[46:49], v[102:105], v[216:219], v[46:49]
	v_mfma_f32_16x16x32_bf16 v[42:45], v[168:171], v[216:219], v[42:45]
	v_mfma_f32_16x16x32_bf16 v[70:73], v[152:155], v[196:199], v[70:73]
	v_mfma_f32_16x16x32_bf16 v[66:69], v[172:175], v[196:199], v[66:69]
	v_mfma_f32_16x16x32_bf16 v[62:65], v[152:155], v[204:207], v[62:65]
	v_mfma_f32_16x16x32_bf16 v[58:61], v[172:175], v[204:207], v[58:61]
	v_mfma_f32_16x16x32_bf16 v[54:57], v[152:155], v[212:215], v[54:57]
	v_mfma_f32_16x16x32_bf16 v[50:53], v[172:175], v[212:215], v[50:53]
	v_mfma_f32_16x16x32_bf16 v[46:49], v[152:155], v[220:223], v[46:49]
	v_mfma_f32_16x16x32_bf16 v[42:45], v[172:175], v[220:223], v[42:45]
	v_mfma_f32_16x16x32_bf16 v[134:137], v[176:179], v[192:195], v[134:137]
	v_mfma_f32_16x16x32_bf16 v[130:133], v[184:187], v[192:195], v[130:133]
	v_mfma_f32_16x16x32_bf16 v[126:129], v[176:179], v[200:203], v[126:129]
	v_mfma_f32_16x16x32_bf16 v[122:125], v[184:187], v[200:203], v[122:125]
	v_mfma_f32_16x16x32_bf16 v[118:121], v[176:179], v[208:211], v[118:121]
	v_mfma_f32_16x16x32_bf16 v[114:117], v[184:187], v[208:211], v[114:117]
	v_mfma_f32_16x16x32_bf16 v[110:113], v[176:179], v[216:219], v[110:113]
	v_mfma_f32_16x16x32_bf16 v[106:109], v[184:187], v[216:219], v[106:109]
	v_mfma_f32_16x16x32_bf16 v[134:137], v[180:183], v[196:199], v[134:137]
	v_mfma_f32_16x16x32_bf16 v[130:133], v[188:191], v[196:199], v[130:133]
	v_mfma_f32_16x16x32_bf16 v[126:129], v[180:183], v[204:207], v[126:129]
	v_mfma_f32_16x16x32_bf16 v[122:125], v[188:191], v[204:207], v[122:125]
	v_mfma_f32_16x16x32_bf16 v[118:121], v[180:183], v[212:215], v[118:121]
	v_mfma_f32_16x16x32_bf16 v[114:117], v[188:191], v[212:215], v[114:117]
	v_mfma_f32_16x16x32_bf16 v[110:113], v[180:183], v[220:223], v[110:113]
	v_mfma_f32_16x16x32_bf16 v[106:109], v[188:191], v[220:223], v[106:109]
	s_barrier
	s_add_i32 s2, s2, s48
	v_lshl_add_u64 v[156:157], v[156:157], 0, s[20:21]
	s_mov_b32 m0, s2
	ds_read_b128 v[192:195], v164 offset:49152
	ds_read_b128 v[196:199], v164 offset:50176
	ds_read_b128 v[200:203], v164 offset:51200
	ds_read_b128 v[204:207], v164 offset:52224
	ds_read_b128 v[208:211], v164 offset:53248
	ds_read_b128 v[212:215], v164 offset:54272
	ds_read_b128 v[216:219], v164 offset:55296
	ds_read_b128 v[220:223], v164 offset:56320
	global_load_lds_dwordx4 v[156:157], off
	s_add_i32 m0, s2, 0x2000
	s_add_u32 s6, s6, 0x80080
	v_lshl_add_u64 v[156:157], v[226:227], 0, s[20:21]
	s_addc_u32 s7, s7, 0
	s_add_i32 s2, s44, s48
	global_load_lds_dwordx4 v[156:157], off
	v_lshl_add_u64 v[156:157], s[6:7], 0, v[140:141]
	s_mov_b32 m0, s2
	s_nop 0
	global_load_lds_dwordx4 v[156:157], off
	v_lshl_add_u64 v[156:157], s[6:7], 0, v[144:145]
	s_add_i32 m0, s2, 0x2000
	s_nop 0
	global_load_lds_dwordx4 v[156:157], off
	v_lshl_add_u64 v[156:157], v[228:229], 0, s[20:21]
	s_mov_b32 m0, s67
	s_nop 0
	global_load_lds_dwordx4 v[156:157], off
	v_lshl_add_u64 v[156:157], v[230:231], 0, s[20:21]
	s_mov_b32 m0, s68
	s_nop 0
	global_load_lds_dwordx4 v[156:157], off
	s_waitcnt vmcnt(8)
	s_waitcnt lgkmcnt(0)
	s_barrier
	s_waitcnt lgkmcnt(0)
	v_mfma_f32_16x16x32_bf16 v[34:37], v[102:105], v[192:195], v[34:37]
	v_mfma_f32_16x16x32_bf16 v[26:29], v[168:171], v[192:195], v[26:29]
	v_mfma_f32_16x16x32_bf16 v[22:25], v[102:105], v[200:203], v[22:25]
	v_mfma_f32_16x16x32_bf16 v[18:21], v[168:171], v[200:203], v[18:21]
	v_mfma_f32_16x16x32_bf16 v[14:17], v[102:105], v[208:211], v[14:17]
	v_mfma_f32_16x16x32_bf16 v[10:13], v[168:171], v[208:211], v[10:13]
	v_mfma_f32_16x16x32_bf16 v[6:9], v[102:105], v[216:219], v[6:9]
	v_mfma_f32_16x16x32_bf16 v[2:5], v[168:171], v[216:219], v[2:5]
	v_mfma_f32_16x16x32_bf16 v[34:37], v[152:155], v[196:199], v[34:37]
	v_mfma_f32_16x16x32_bf16 v[26:29], v[172:175], v[196:199], v[26:29]
	v_mfma_f32_16x16x32_bf16 v[22:25], v[152:155], v[204:207], v[22:25]
	v_mfma_f32_16x16x32_bf16 v[18:21], v[172:175], v[204:207], v[18:21]
	v_mfma_f32_16x16x32_bf16 v[14:17], v[152:155], v[212:215], v[14:17]
	v_mfma_f32_16x16x32_bf16 v[10:13], v[172:175], v[212:215], v[10:13]
	v_mfma_f32_16x16x32_bf16 v[6:9], v[152:155], v[220:223], v[6:9]
	v_mfma_f32_16x16x32_bf16 v[2:5], v[172:175], v[220:223], v[2:5]
	v_mfma_f32_16x16x32_bf16 v[94:97], v[176:179], v[192:195], v[94:97]
	v_mfma_f32_16x16x32_bf16 v[102:105], v[180:183], v[196:199], v[94:97]
	v_mfma_f32_16x16x32_bf16 v[94:97], v[184:187], v[192:195], v[98:101]
	v_mfma_f32_16x16x32_bf16 v[86:89], v[176:179], v[200:203], v[86:89]
	v_mfma_f32_16x16x32_bf16 v[82:85], v[184:187], v[200:203], v[82:85]
	v_mfma_f32_16x16x32_bf16 v[78:81], v[176:179], v[208:211], v[78:81]
	v_mfma_f32_16x16x32_bf16 v[74:77], v[184:187], v[208:211], v[74:77]
	v_mfma_f32_16x16x32_bf16 v[38:41], v[176:179], v[216:219], v[38:41]
	v_mfma_f32_16x16x32_bf16 v[30:33], v[184:187], v[216:219], v[30:33]
	v_mfma_f32_16x16x32_bf16 v[98:101], v[188:191], v[196:199], v[94:97]
	v_mfma_f32_16x16x32_bf16 v[86:89], v[180:183], v[204:207], v[86:89]
	v_mfma_f32_16x16x32_bf16 v[82:85], v[188:191], v[204:207], v[82:85]
	v_mfma_f32_16x16x32_bf16 v[78:81], v[180:183], v[212:215], v[78:81]
	v_mfma_f32_16x16x32_bf16 v[74:77], v[188:191], v[212:215], v[74:77]
	v_mfma_f32_16x16x32_bf16 v[38:41], v[180:183], v[220:223], v[38:41]
	v_mfma_f32_16x16x32_bf16 v[30:33], v[188:191], v[220:223], v[30:33]
	s_barrier
	s_add_i32 s2, s80, 2
	s_cmp_gt_u32 s80, 29
	s_cbranch_scc1 .LBB0_259
	s_mov_b32 s80, s2
	s_branch .LBB0_237

.LBB0_711:
	ds_read_b128 v[98:101], v168
	ds_read_b128 v[102:105], v168 offset:1024
	ds_read_b128 v[156:159], v168 offset:2048
	ds_read_b128 v[172:175], v168 offset:3072
	ds_read_b128 v[176:179], v169
	ds_read_b128 v[180:183], v169 offset:1024
	ds_read_b128 v[184:187], v169 offset:2048
	ds_read_b128 v[188:191], v169 offset:3072
	s_add_u32 s26, s6, 0xfff80080
	s_addc_u32 s27, s7, -1
	s_cmp_eq_u32 s58, 28
	s_cselect_b32 s29, s5, s27
	s_cselect_b32 s28, s21, s26
	s_cselect_b32 s27, s19, s57
	s_cselect_b32 s26, s51, s56
	v_lshl_add_u64 v[160:161], s[6:7], 0, v[152:153]
	s_add_i32 m0, s36, 0xc000
	ds_read_b128 v[192:195], v170
	ds_read_b128 v[196:199], v170 offset:1024
	ds_read_b128 v[200:203], v170 offset:2048
	ds_read_b128 v[204:207], v170 offset:3072
	ds_read_b128 v[208:211], v170 offset:4096
	ds_read_b128 v[212:215], v170 offset:5120
	ds_read_b128 v[216:219], v170 offset:6144
	ds_read_b128 v[220:223], v170 offset:7168
	global_load_lds_dwordx4 v[160:161], off
	v_lshl_add_u64 v[160:161], s[6:7], 0, v[154:155]
	s_add_i32 m0, s36, 0xe000
	s_nop 0
	global_load_lds_dwordx4 v[160:161], off
	s_waitcnt vmcnt(8)
	s_waitcnt lgkmcnt(0)
	s_barrier
	s_waitcnt lgkmcnt(0)
	v_mfma_f32_16x16x32_bf16 v[70:73], v[98:101], v[192:195], v[70:73]
	v_mfma_f32_16x16x32_bf16 v[66:69], v[156:159], v[192:195], v[66:69]
	v_mfma_f32_16x16x32_bf16 v[62:65], v[98:101], v[200:203], v[62:65]
	v_mfma_f32_16x16x32_bf16 v[58:61], v[156:159], v[200:203], v[58:61]
	v_mfma_f32_16x16x32_bf16 v[54:57], v[98:101], v[208:211], v[54:57]
	v_mfma_f32_16x16x32_bf16 v[50:53], v[156:159], v[208:211], v[50:53]
	v_mfma_f32_16x16x32_bf16 v[46:49], v[98:101], v[216:219], v[46:49]
	v_mfma_f32_16x16x32_bf16 v[42:45], v[156:159], v[216:219], v[42:45]
	v_mfma_f32_16x16x32_bf16 v[70:73], v[102:105], v[196:199], v[70:73]
	v_mfma_f32_16x16x32_bf16 v[66:69], v[172:175], v[196:199], v[66:69]
	v_mfma_f32_16x16x32_bf16 v[62:65], v[102:105], v[204:207], v[62:65]
	v_mfma_f32_16x16x32_bf16 v[58:61], v[172:175], v[204:207], v[58:61]
	v_mfma_f32_16x16x32_bf16 v[54:57], v[102:105], v[212:215], v[54:57]
	v_mfma_f32_16x16x32_bf16 v[50:53], v[172:175], v[212:215], v[50:53]
	v_mfma_f32_16x16x32_bf16 v[46:49], v[102:105], v[220:223], v[46:49]
	v_mfma_f32_16x16x32_bf16 v[42:45], v[172:175], v[220:223], v[42:45]
	v_mfma_f32_16x16x32_bf16 v[134:137], v[176:179], v[192:195], v[134:137]
	v_mfma_f32_16x16x32_bf16 v[130:133], v[184:187], v[192:195], v[130:133]
	v_mfma_f32_16x16x32_bf16 v[126:129], v[176:179], v[200:203], v[126:129]
	v_mfma_f32_16x16x32_bf16 v[122:125], v[184:187], v[200:203], v[122:125]
	v_mfma_f32_16x16x32_bf16 v[118:121], v[176:179], v[208:211], v[118:121]
	v_mfma_f32_16x16x32_bf16 v[114:117], v[184:187], v[208:211], v[114:117]
	v_mfma_f32_16x16x32_bf16 v[110:113], v[176:179], v[216:219], v[110:113]
	v_mfma_f32_16x16x32_bf16 v[106:109], v[184:187], v[216:219], v[106:109]
	v_mfma_f32_16x16x32_bf16 v[134:137], v[180:183], v[196:199], v[134:137]
	v_mfma_f32_16x16x32_bf16 v[130:133], v[188:191], v[196:199], v[130:133]
	v_mfma_f32_16x16x32_bf16 v[126:129], v[180:183], v[204:207], v[126:129]
	v_mfma_f32_16x16x32_bf16 v[122:125], v[188:191], v[204:207], v[122:125]
	v_mfma_f32_16x16x32_bf16 v[118:121], v[180:183], v[212:215], v[118:121]
	v_mfma_f32_16x16x32_bf16 v[114:117], v[188:191], v[212:215], v[114:117]
	v_mfma_f32_16x16x32_bf16 v[110:113], v[180:183], v[220:223], v[110:113]
	v_mfma_f32_16x16x32_bf16 v[106:109], v[188:191], v[220:223], v[106:109]
	s_barrier
	s_add_i32 s59, s42, s35
	v_lshl_add_u64 v[160:161], s[26:27], 0, v[140:141]
	s_mov_b32 m0, s59
	ds_read_b128 v[192:195], v170 offset:16384
	ds_read_b128 v[196:199], v170 offset:17408
	ds_read_b128 v[200:203], v170 offset:18432
	ds_read_b128 v[204:207], v170 offset:19456
	ds_read_b128 v[208:211], v170 offset:20480
	ds_read_b128 v[212:215], v170 offset:21504
	ds_read_b128 v[216:219], v170 offset:22528
	ds_read_b128 v[220:223], v170 offset:23552
	global_load_lds_dwordx4 v[160:161], off
	s_add_i32 m0, s59, 0x2000
	s_add_u32 s60, s26, 0x80000
	v_lshl_add_u64 v[224:225], s[26:27], 0, v[144:145]
	s_addc_u32 s61, s27, 0
	s_add_i32 s59, s48, s35
	global_load_lds_dwordx4 v[224:225], off
	v_lshl_add_u64 v[226:227], s[60:61], 0, v[140:141]
	s_mov_b32 m0, s59
	v_lshl_add_u64 v[228:229], s[28:29], 0, v[142:143]
	global_load_lds_dwordx4 v[226:227], off
	v_lshl_add_u64 v[226:227], s[60:61], 0, v[144:145]
	s_add_i32 m0, s59, 0x2000
	s_nop 0
	global_load_lds_dwordx4 v[226:227], off
	v_lshl_add_u64 v[226:227], s[28:29], 0, v[138:139]
	s_mov_b32 m0, s36
	s_nop 0
	global_load_lds_dwordx4 v[226:227], off
	s_mov_b32 m0, s37
	s_nop 0
	global_load_lds_dwordx4 v[228:229], off
	s_waitcnt vmcnt(8)
	s_waitcnt lgkmcnt(0)
	s_barrier
	s_waitcnt lgkmcnt(0)
	v_mfma_f32_16x16x32_bf16 v[34:37], v[98:101], v[192:195], v[34:37]
	v_mfma_f32_16x16x32_bf16 v[26:29], v[156:159], v[192:195], v[26:29]
	v_mfma_f32_16x16x32_bf16 v[22:25], v[98:101], v[200:203], v[22:25]
	v_mfma_f32_16x16x32_bf16 v[18:21], v[156:159], v[200:203], v[18:21]
	v_mfma_f32_16x16x32_bf16 v[14:17], v[98:101], v[208:211], v[14:17]
	v_mfma_f32_16x16x32_bf16 v[10:13], v[156:159], v[208:211], v[10:13]
	v_mfma_f32_16x16x32_bf16 v[6:9], v[98:101], v[216:219], v[6:9]
	v_mfma_f32_16x16x32_bf16 v[2:5], v[156:159], v[216:219], v[2:5]
	v_mfma_f32_16x16x32_bf16 v[34:37], v[102:105], v[196:199], v[34:37]
	v_mfma_f32_16x16x32_bf16 v[26:29], v[172:175], v[196:199], v[26:29]
	v_mfma_f32_16x16x32_bf16 v[22:25], v[102:105], v[204:207], v[22:25]
	v_mfma_f32_16x16x32_bf16 v[18:21], v[172:175], v[204:207], v[18:21]
	v_mfma_f32_16x16x32_bf16 v[14:17], v[102:105], v[212:215], v[14:17]
	v_mfma_f32_16x16x32_bf16 v[10:13], v[172:175], v[212:215], v[10:13]
	v_mfma_f32_16x16x32_bf16 v[6:9], v[102:105], v[220:223], v[6:9]
	v_mfma_f32_16x16x32_bf16 v[2:5], v[172:175], v[220:223], v[2:5]
	v_mfma_f32_16x16x32_bf16 v[94:97], v[176:179], v[192:195], v[94:97]
	v_mfma_f32_16x16x32_bf16 v[90:93], v[184:187], v[192:195], v[90:93]
	v_mfma_f32_16x16x32_bf16 v[86:89], v[176:179], v[200:203], v[86:89]
	v_mfma_f32_16x16x32_bf16 v[82:85], v[184:187], v[200:203], v[82:85]
	v_mfma_f32_16x16x32_bf16 v[78:81], v[176:179], v[208:211], v[78:81]
	v_mfma_f32_16x16x32_bf16 v[74:77], v[184:187], v[208:211], v[74:77]
	v_mfma_f32_16x16x32_bf16 v[38:41], v[176:179], v[216:219], v[38:41]
	v_mfma_f32_16x16x32_bf16 v[30:33], v[184:187], v[216:219], v[30:33]
	v_mfma_f32_16x16x32_bf16 v[94:97], v[180:183], v[196:199], v[94:97]
	v_mfma_f32_16x16x32_bf16 v[90:93], v[188:191], v[196:199], v[90:93]
	v_mfma_f32_16x16x32_bf16 v[86:89], v[180:183], v[204:207], v[86:89]
	v_mfma_f32_16x16x32_bf16 v[82:85], v[188:191], v[204:207], v[82:85]
	v_mfma_f32_16x16x32_bf16 v[78:81], v[180:183], v[212:215], v[78:81]
	v_mfma_f32_16x16x32_bf16 v[74:77], v[188:191], v[212:215], v[74:77]
	v_mfma_f32_16x16x32_bf16 v[38:41], v[180:183], v[220:223], v[38:41]
	v_mfma_f32_16x16x32_bf16 v[30:33], v[188:191], v[220:223], v[30:33]
	s_barrier
	s_add_i32 s59, 0, 0x18000
	v_add_u32_e32 v171, s59, v166
	s_add_i32 s60, 0, 0x1c000
	ds_read_b128 v[98:101], v171
	ds_read_b128 v[102:105], v171 offset:1024
	ds_read_b128 v[156:159], v171 offset:2048
	ds_read_b128 v[172:175], v171 offset:3072
	v_add_u32_e32 v171, s60, v166
	ds_read_b128 v[176:179], v171
	ds_read_b128 v[180:183], v171 offset:1024
	ds_read_b128 v[184:187], v171 offset:2048
	ds_read_b128 v[188:191], v171 offset:3072
	s_add_u32 s28, s28, 0x80000
	s_addc_u32 s29, s29, 0
	s_mov_b32 m0, s38
	v_lshl_add_u64 v[230:231], s[28:29], 0, v[138:139]
	ds_read_b128 v[192:195], v170 offset:32768
	ds_read_b128 v[196:199], v170 offset:33792
	ds_read_b128 v[200:203], v170 offset:34816
	ds_read_b128 v[204:207], v170 offset:35840
	ds_read_b128 v[208:211], v170 offset:36864
	ds_read_b128 v[212:215], v170 offset:37888
	ds_read_b128 v[216:219], v170 offset:38912
	ds_read_b128 v[220:223], v170 offset:39936
	global_load_lds_dwordx4 v[230:231], off
	v_lshl_add_u64 v[230:231], s[28:29], 0, v[142:143]
	s_mov_b32 m0, s39
	s_nop 0
	global_load_lds_dwordx4 v[230:231], off
	s_waitcnt vmcnt(8)
	s_waitcnt lgkmcnt(0)
	s_barrier
	s_waitcnt lgkmcnt(0)
	v_mfma_f32_16x16x32_bf16 v[70:73], v[98:101], v[192:195], v[70:73]
	v_mfma_f32_16x16x32_bf16 v[66:69], v[156:159], v[192:195], v[66:69]
	v_mfma_f32_16x16x32_bf16 v[62:65], v[98:101], v[200:203], v[62:65]
	v_mfma_f32_16x16x32_bf16 v[58:61], v[156:159], v[200:203], v[58:61]
	v_mfma_f32_16x16x32_bf16 v[54:57], v[98:101], v[208:211], v[54:57]
	v_mfma_f32_16x16x32_bf16 v[50:53], v[156:159], v[208:211], v[50:53]
	v_mfma_f32_16x16x32_bf16 v[46:49], v[98:101], v[216:219], v[46:49]
	v_mfma_f32_16x16x32_bf16 v[42:45], v[156:159], v[216:219], v[42:45]
	v_mfma_f32_16x16x32_bf16 v[70:73], v[102:105], v[196:199], v[70:73]
	v_mfma_f32_16x16x32_bf16 v[66:69], v[172:175], v[196:199], v[66:69]
	v_mfma_f32_16x16x32_bf16 v[62:65], v[102:105], v[204:207], v[62:65]
	v_mfma_f32_16x16x32_bf16 v[58:61], v[172:175], v[204:207], v[58:61]
	v_mfma_f32_16x16x32_bf16 v[54:57], v[102:105], v[212:215], v[54:57]
	v_mfma_f32_16x16x32_bf16 v[50:53], v[172:175], v[212:215], v[50:53]
	v_mfma_f32_16x16x32_bf16 v[46:49], v[102:105], v[220:223], v[46:49]
	v_mfma_f32_16x16x32_bf16 v[42:45], v[172:175], v[220:223], v[42:45]
	v_mfma_f32_16x16x32_bf16 v[134:137], v[176:179], v[192:195], v[134:137]
	v_mfma_f32_16x16x32_bf16 v[130:133], v[184:187], v[192:195], v[130:133]
	v_mfma_f32_16x16x32_bf16 v[126:129], v[176:179], v[200:203], v[126:129]
	v_mfma_f32_16x16x32_bf16 v[122:125], v[184:187], v[200:203], v[122:125]
	v_mfma_f32_16x16x32_bf16 v[118:121], v[176:179], v[208:211], v[118:121]
	v_mfma_f32_16x16x32_bf16 v[114:117], v[184:187], v[208:211], v[114:117]
	v_mfma_f32_16x16x32_bf16 v[110:113], v[176:179], v[216:219], v[110:113]
	v_mfma_f32_16x16x32_bf16 v[106:109], v[184:187], v[216:219], v[106:109]
	v_mfma_f32_16x16x32_bf16 v[134:137], v[180:183], v[196:199], v[134:137]
	v_mfma_f32_16x16x32_bf16 v[130:133], v[188:191], v[196:199], v[130:133]
	v_mfma_f32_16x16x32_bf16 v[126:129], v[180:183], v[204:207], v[126:129]
	v_mfma_f32_16x16x32_bf16 v[122:125], v[188:191], v[204:207], v[122:125]
	v_mfma_f32_16x16x32_bf16 v[118:121], v[180:183], v[212:215], v[118:121]
	v_mfma_f32_16x16x32_bf16 v[114:117], v[188:191], v[212:215], v[114:117]
	v_mfma_f32_16x16x32_bf16 v[110:113], v[180:183], v[220:223], v[110:113]
	v_mfma_f32_16x16x32_bf16 v[106:109], v[188:191], v[220:223], v[106:109]
	s_barrier
	s_add_i32 s28, s59, s35
	v_lshl_add_u64 v[160:161], v[160:161], 0, s[8:9]
	s_mov_b32 m0, s28
	ds_read_b128 v[192:195], v170 offset:49152
	ds_read_b128 v[196:199], v170 offset:50176
	ds_read_b128 v[200:203], v170 offset:51200
	ds_read_b128 v[204:207], v170 offset:52224
	ds_read_b128 v[208:211], v170 offset:53248
	ds_read_b128 v[212:215], v170 offset:54272
	ds_read_b128 v[216:219], v170 offset:55296
	ds_read_b128 v[220:223], v170 offset:56320
	global_load_lds_dwordx4 v[160:161], off
	s_add_i32 m0, s28, 0x2000
	s_add_u32 s26, s26, 0x80080
	v_lshl_add_u64 v[160:161], v[224:225], 0, s[8:9]
	s_addc_u32 s27, s27, 0
	s_add_i32 s28, s60, s35
	global_load_lds_dwordx4 v[160:161], off
	v_lshl_add_u64 v[160:161], s[26:27], 0, v[140:141]
	s_mov_b32 m0, s28
	s_nop 0
	global_load_lds_dwordx4 v[160:161], off
	v_lshl_add_u64 v[160:161], s[26:27], 0, v[144:145]
	s_add_i32 m0, s28, 0x2000
	s_nop 0
	global_load_lds_dwordx4 v[160:161], off
	v_lshl_add_u64 v[160:161], v[226:227], 0, s[8:9]
	s_mov_b32 m0, s40
	s_nop 0
	global_load_lds_dwordx4 v[160:161], off
	v_lshl_add_u64 v[160:161], v[228:229], 0, s[8:9]
	s_mov_b32 m0, s41
	s_nop 0
	global_load_lds_dwordx4 v[160:161], off
	s_waitcnt vmcnt(8)
	s_waitcnt lgkmcnt(0)
	s_barrier
	s_waitcnt lgkmcnt(0)
	v_mfma_f32_16x16x32_bf16 v[34:37], v[98:101], v[192:195], v[34:37]
	v_mfma_f32_16x16x32_bf16 v[26:29], v[156:159], v[192:195], v[26:29]
	v_mfma_f32_16x16x32_bf16 v[22:25], v[98:101], v[200:203], v[22:25]
	v_mfma_f32_16x16x32_bf16 v[18:21], v[156:159], v[200:203], v[18:21]
	v_mfma_f32_16x16x32_bf16 v[14:17], v[98:101], v[208:211], v[14:17]
	v_mfma_f32_16x16x32_bf16 v[10:13], v[156:159], v[208:211], v[10:13]
	v_mfma_f32_16x16x32_bf16 v[6:9], v[98:101], v[216:219], v[6:9]
	v_mfma_f32_16x16x32_bf16 v[2:5], v[156:159], v[216:219], v[2:5]
	v_mfma_f32_16x16x32_bf16 v[34:37], v[102:105], v[196:199], v[34:37]
	v_mfma_f32_16x16x32_bf16 v[26:29], v[172:175], v[196:199], v[26:29]
	v_mfma_f32_16x16x32_bf16 v[22:25], v[102:105], v[204:207], v[22:25]
	v_mfma_f32_16x16x32_bf16 v[18:21], v[172:175], v[204:207], v[18:21]
	v_mfma_f32_16x16x32_bf16 v[14:17], v[102:105], v[212:215], v[14:17]
	v_mfma_f32_16x16x32_bf16 v[10:13], v[172:175], v[212:215], v[10:13]
	v_mfma_f32_16x16x32_bf16 v[6:9], v[102:105], v[220:223], v[6:9]
	v_mfma_f32_16x16x32_bf16 v[2:5], v[172:175], v[220:223], v[2:5]
	v_mfma_f32_16x16x32_bf16 v[94:97], v[176:179], v[192:195], v[94:97]
	v_mfma_f32_16x16x32_bf16 v[90:93], v[184:187], v[192:195], v[90:93]
	v_mfma_f32_16x16x32_bf16 v[86:89], v[176:179], v[200:203], v[86:89]
	v_mfma_f32_16x16x32_bf16 v[82:85], v[184:187], v[200:203], v[82:85]
	v_mfma_f32_16x16x32_bf16 v[78:81], v[176:179], v[208:211], v[78:81]
	v_mfma_f32_16x16x32_bf16 v[74:77], v[184:187], v[208:211], v[74:77]
	v_mfma_f32_16x16x32_bf16 v[38:41], v[176:179], v[216:219], v[38:41]
	v_mfma_f32_16x16x32_bf16 v[30:33], v[184:187], v[216:219], v[30:33]
	v_mfma_f32_16x16x32_bf16 v[94:97], v[180:183], v[196:199], v[94:97]
	v_mfma_f32_16x16x32_bf16 v[90:93], v[188:191], v[196:199], v[90:93]
	v_mfma_f32_16x16x32_bf16 v[86:89], v[180:183], v[204:207], v[86:89]
	v_mfma_f32_16x16x32_bf16 v[82:85], v[188:191], v[204:207], v[82:85]
	v_mfma_f32_16x16x32_bf16 v[78:81], v[180:183], v[212:215], v[78:81]
	v_mfma_f32_16x16x32_bf16 v[74:77], v[188:191], v[212:215], v[74:77]
	v_mfma_f32_16x16x32_bf16 v[38:41], v[180:183], v[220:223], v[38:41]
	v_mfma_f32_16x16x32_bf16 v[30:33], v[188:191], v[220:223], v[30:33]
	s_barrier
	s_add_i32 s58, s58, 2
	s_add_u32 s6, s6, 0x100
	s_addc_u32 s7, s7, 0
	s_add_u32 s56, s56, 0x100
	s_addc_u32 s57, s57, 0
	s_cmp_gt_u32 s58, 29
	s_cbranch_scc0 .LBB0_711
	s_and_b64 vcc, exec, s[10:11]
	s_cbranch_vccz .LBB0_715
	s_barrier
	v_lshl_add_u32 v156, s0, 8, v165
	s_cmp_lg_u32 s4, 48
	s_mov_b64 s[6:7], -1
	s_cbranch_scc1 .LBB0_716

.LBB0_952:
	v_add_u32_e32 v154, s40, v158
	ds_read_b128 v[150:153], v154
	ds_read_b128 v[162:165], v154 offset:1024
	ds_read_b128 v[166:169], v154 offset:2048
	ds_read_b128 v[170:173], v154 offset:3072
	v_add_u32_e32 v154, s41, v158
	s_add_u32 s22, s18, s20
	ds_read_b128 v[174:177], v154
	ds_read_b128 v[178:181], v154 offset:1024
	ds_read_b128 v[182:185], v154 offset:2048
	ds_read_b128 v[186:189], v154 offset:3072
	s_addc_u32 s23, s19, s21
	s_add_u32 s22, s22, 0x100
	s_addc_u32 s23, s23, 0
	s_add_u32 s51, s48, s20
	s_addc_u32 s52, s49, s21
	s_cmpk_eq_i32 s20, 0x2f00
	s_cselect_b32 s25, s5, s23
	s_cselect_b32 s24, s4, s22
	s_cselect_b32 s23, s17, s52
	s_cselect_b32 s22, s16, s51
	v_lshl_add_u64 v[154:155], v[146:147], 0, s[20:21]
	s_add_i32 m0, s28, 0xc000
	ds_read_b128 v[190:193], v160
	ds_read_b128 v[194:197], v160 offset:1024
	ds_read_b128 v[198:201], v160 offset:2048
	ds_read_b128 v[202:205], v160 offset:3072
	ds_read_b128 v[206:209], v160 offset:4096
	ds_read_b128 v[210:213], v160 offset:5120
	ds_read_b128 v[214:217], v160 offset:6144
	ds_read_b128 v[218:221], v160 offset:7168
	global_load_lds_dwordx4 v[154:155], off
	v_lshl_add_u64 v[154:155], v[148:149], 0, s[20:21]
	s_add_i32 m0, s28, 0xe000
	s_nop 0
	global_load_lds_dwordx4 v[154:155], off
	s_waitcnt vmcnt(8)
	s_waitcnt lgkmcnt(0)
	s_barrier
	s_waitcnt lgkmcnt(0)
	v_mfma_f32_16x16x32_bf16 v[126:129], v[150:153], v[190:193], v[126:129]
	v_mfma_f32_16x16x32_bf16 v[122:125], v[166:169], v[190:193], v[122:125]
	v_mfma_f32_16x16x32_bf16 v[114:117], v[150:153], v[198:201], v[114:117]
	v_mfma_f32_16x16x32_bf16 v[106:109], v[166:169], v[198:201], v[106:109]
	v_mfma_f32_16x16x32_bf16 v[98:101], v[150:153], v[206:209], v[98:101]
	v_mfma_f32_16x16x32_bf16 v[90:93], v[166:169], v[206:209], v[90:93]
	v_mfma_f32_16x16x32_bf16 v[82:85], v[150:153], v[214:217], v[82:85]
	v_mfma_f32_16x16x32_bf16 v[74:77], v[166:169], v[214:217], v[74:77]
	v_mfma_f32_16x16x32_bf16 v[126:129], v[162:165], v[194:197], v[126:129]
	v_mfma_f32_16x16x32_bf16 v[122:125], v[170:173], v[194:197], v[122:125]
	v_mfma_f32_16x16x32_bf16 v[114:117], v[162:165], v[202:205], v[114:117]
	v_mfma_f32_16x16x32_bf16 v[106:109], v[170:173], v[202:205], v[106:109]
	v_mfma_f32_16x16x32_bf16 v[98:101], v[162:165], v[210:213], v[98:101]
	v_mfma_f32_16x16x32_bf16 v[90:93], v[170:173], v[210:213], v[90:93]
	v_mfma_f32_16x16x32_bf16 v[82:85], v[162:165], v[218:221], v[82:85]
	v_mfma_f32_16x16x32_bf16 v[74:77], v[170:173], v[218:221], v[74:77]
	v_mfma_f32_16x16x32_bf16 v[118:121], v[174:177], v[190:193], v[118:121]
	v_mfma_f32_16x16x32_bf16 v[110:113], v[182:185], v[190:193], v[110:113]
	v_mfma_f32_16x16x32_bf16 v[102:105], v[174:177], v[198:201], v[102:105]
	v_mfma_f32_16x16x32_bf16 v[94:97], v[182:185], v[198:201], v[94:97]
	v_mfma_f32_16x16x32_bf16 v[86:89], v[174:177], v[206:209], v[86:89]
	v_mfma_f32_16x16x32_bf16 v[78:81], v[182:185], v[206:209], v[78:81]
	v_mfma_f32_16x16x32_bf16 v[70:73], v[174:177], v[214:217], v[70:73]
	v_mfma_f32_16x16x32_bf16 v[66:69], v[182:185], v[214:217], v[66:69]
	v_mfma_f32_16x16x32_bf16 v[118:121], v[178:181], v[194:197], v[118:121]
	v_mfma_f32_16x16x32_bf16 v[110:113], v[186:189], v[194:197], v[110:113]
	v_mfma_f32_16x16x32_bf16 v[102:105], v[178:181], v[202:205], v[102:105]
	v_mfma_f32_16x16x32_bf16 v[94:97], v[186:189], v[202:205], v[94:97]
	v_mfma_f32_16x16x32_bf16 v[86:89], v[178:181], v[210:213], v[86:89]
	v_mfma_f32_16x16x32_bf16 v[78:81], v[186:189], v[210:213], v[78:81]
	v_mfma_f32_16x16x32_bf16 v[70:73], v[178:181], v[218:221], v[70:73]
	v_mfma_f32_16x16x32_bf16 v[66:69], v[186:189], v[218:221], v[66:69]
	s_barrier
	s_add_i32 s51, s40, s27
	v_lshl_add_u64 v[154:155], s[22:23], 0, v[132:133]
	s_mov_b32 m0, s51
	ds_read_b128 v[190:193], v160 offset:16384
	ds_read_b128 v[194:197], v160 offset:17408
	ds_read_b128 v[198:201], v160 offset:18432
	ds_read_b128 v[202:205], v160 offset:19456
	ds_read_b128 v[206:209], v160 offset:20480
	ds_read_b128 v[210:213], v160 offset:21504
	ds_read_b128 v[214:217], v160 offset:22528
	ds_read_b128 v[218:221], v160 offset:23552
	global_load_lds_dwordx4 v[154:155], off
	s_add_i32 m0, s51, 0x2000
	s_add_u32 s52, s22, 0x180000
	v_lshl_add_u64 v[222:223], s[22:23], 0, v[136:137]
	s_addc_u32 s53, s23, 0
	s_add_i32 s51, s41, s27
	global_load_lds_dwordx4 v[222:223], off
	v_lshl_add_u64 v[224:225], s[52:53], 0, v[132:133]
	s_mov_b32 m0, s51
	v_lshl_add_u64 v[226:227], s[24:25], 0, v[134:135]
	global_load_lds_dwordx4 v[224:225], off
	v_lshl_add_u64 v[224:225], s[52:53], 0, v[136:137]
	s_add_i32 m0, s51, 0x2000
	s_nop 0
	global_load_lds_dwordx4 v[224:225], off
	v_lshl_add_u64 v[224:225], s[24:25], 0, v[130:131]
	s_mov_b32 m0, s28
	s_nop 0
	global_load_lds_dwordx4 v[224:225], off
	s_mov_b32 m0, s29
	s_nop 0
	global_load_lds_dwordx4 v[226:227], off
	s_waitcnt vmcnt(8)
	s_waitcnt lgkmcnt(0)
	s_barrier
	s_waitcnt lgkmcnt(0)
	v_mfma_f32_16x16x32_bf16 v[62:65], v[150:153], v[190:193], v[62:65]
	v_mfma_f32_16x16x32_bf16 v[58:61], v[166:169], v[190:193], v[58:61]
	v_mfma_f32_16x16x32_bf16 v[50:53], v[150:153], v[198:201], v[50:53]
	v_mfma_f32_16x16x32_bf16 v[42:45], v[166:169], v[198:201], v[42:45]
	v_mfma_f32_16x16x32_bf16 v[34:37], v[150:153], v[206:209], v[34:37]
	v_mfma_f32_16x16x32_bf16 v[26:29], v[166:169], v[206:209], v[26:29]
	v_mfma_f32_16x16x32_bf16 v[18:21], v[150:153], v[214:217], v[18:21]
	v_mfma_f32_16x16x32_bf16 v[10:13], v[166:169], v[214:217], v[10:13]
	v_mfma_f32_16x16x32_bf16 v[62:65], v[162:165], v[194:197], v[62:65]
	v_mfma_f32_16x16x32_bf16 v[58:61], v[170:173], v[194:197], v[58:61]
	v_mfma_f32_16x16x32_bf16 v[50:53], v[162:165], v[202:205], v[50:53]
	v_mfma_f32_16x16x32_bf16 v[42:45], v[170:173], v[202:205], v[42:45]
	v_mfma_f32_16x16x32_bf16 v[34:37], v[162:165], v[210:213], v[34:37]
	v_mfma_f32_16x16x32_bf16 v[26:29], v[170:173], v[210:213], v[26:29]
	v_mfma_f32_16x16x32_bf16 v[18:21], v[162:165], v[218:221], v[18:21]
	v_mfma_f32_16x16x32_bf16 v[10:13], v[170:173], v[218:221], v[10:13]
	v_mfma_f32_16x16x32_bf16 v[54:57], v[174:177], v[190:193], v[54:57]
	v_mfma_f32_16x16x32_bf16 v[46:49], v[182:185], v[190:193], v[46:49]
	v_mfma_f32_16x16x32_bf16 v[38:41], v[174:177], v[198:201], v[38:41]
	v_mfma_f32_16x16x32_bf16 v[30:33], v[182:185], v[198:201], v[30:33]
	v_mfma_f32_16x16x32_bf16 v[22:25], v[174:177], v[206:209], v[22:25]
	v_mfma_f32_16x16x32_bf16 v[14:17], v[182:185], v[206:209], v[14:17]
	v_mfma_f32_16x16x32_bf16 v[6:9], v[174:177], v[214:217], v[6:9]
	v_mfma_f32_16x16x32_bf16 v[2:5], v[182:185], v[214:217], v[2:5]
	v_mfma_f32_16x16x32_bf16 v[54:57], v[178:181], v[194:197], v[54:57]
	v_mfma_f32_16x16x32_bf16 v[46:49], v[186:189], v[194:197], v[46:49]
	v_mfma_f32_16x16x32_bf16 v[38:41], v[178:181], v[202:205], v[38:41]
	v_mfma_f32_16x16x32_bf16 v[30:33], v[186:189], v[202:205], v[30:33]
	v_mfma_f32_16x16x32_bf16 v[22:25], v[178:181], v[210:213], v[22:25]
	v_mfma_f32_16x16x32_bf16 v[14:17], v[186:189], v[210:213], v[14:17]
	v_mfma_f32_16x16x32_bf16 v[6:9], v[178:181], v[218:221], v[6:9]
	v_mfma_f32_16x16x32_bf16 v[2:5], v[186:189], v[218:221], v[2:5]
	s_barrier
	s_add_i32 s51, 0, 0x18000
	v_add_u32_e32 v161, s51, v158
	s_add_i32 s52, 0, 0x1c000
	ds_read_b128 v[150:153], v161
	ds_read_b128 v[162:165], v161 offset:1024
	ds_read_b128 v[166:169], v161 offset:2048
	ds_read_b128 v[170:173], v161 offset:3072
	v_add_u32_e32 v161, s52, v158
	ds_read_b128 v[174:177], v161
	ds_read_b128 v[178:181], v161 offset:1024
	ds_read_b128 v[182:185], v161 offset:2048
	ds_read_b128 v[186:189], v161 offset:3072
	s_add_u32 s24, s24, 0x180000
	s_addc_u32 s25, s25, 0
	s_mov_b32 m0, s30
	v_lshl_add_u64 v[228:229], s[24:25], 0, v[130:131]
	ds_read_b128 v[190:193], v160 offset:32768
	ds_read_b128 v[194:197], v160 offset:33792
	ds_read_b128 v[198:201], v160 offset:34816
	ds_read_b128 v[202:205], v160 offset:35840
	ds_read_b128 v[206:209], v160 offset:36864
	ds_read_b128 v[210:213], v160 offset:37888
	ds_read_b128 v[214:217], v160 offset:38912
	ds_read_b128 v[218:221], v160 offset:39936
	global_load_lds_dwordx4 v[228:229], off
	v_lshl_add_u64 v[228:229], s[24:25], 0, v[134:135]
	s_mov_b32 m0, s31
	s_nop 0
	global_load_lds_dwordx4 v[228:229], off
	s_waitcnt vmcnt(8)
	s_waitcnt lgkmcnt(0)
	s_barrier
	s_waitcnt lgkmcnt(0)
	v_mfma_f32_16x16x32_bf16 v[126:129], v[150:153], v[190:193], v[126:129]
	v_mfma_f32_16x16x32_bf16 v[122:125], v[166:169], v[190:193], v[122:125]
	v_mfma_f32_16x16x32_bf16 v[114:117], v[150:153], v[198:201], v[114:117]
	v_mfma_f32_16x16x32_bf16 v[106:109], v[166:169], v[198:201], v[106:109]
	v_mfma_f32_16x16x32_bf16 v[98:101], v[150:153], v[206:209], v[98:101]
	v_mfma_f32_16x16x32_bf16 v[90:93], v[166:169], v[206:209], v[90:93]
	v_mfma_f32_16x16x32_bf16 v[82:85], v[150:153], v[214:217], v[82:85]
	v_mfma_f32_16x16x32_bf16 v[74:77], v[166:169], v[214:217], v[74:77]
	v_mfma_f32_16x16x32_bf16 v[126:129], v[162:165], v[194:197], v[126:129]
	v_mfma_f32_16x16x32_bf16 v[122:125], v[170:173], v[194:197], v[122:125]
	v_mfma_f32_16x16x32_bf16 v[114:117], v[162:165], v[202:205], v[114:117]
	v_mfma_f32_16x16x32_bf16 v[106:109], v[170:173], v[202:205], v[106:109]
	v_mfma_f32_16x16x32_bf16 v[98:101], v[162:165], v[210:213], v[98:101]
	v_mfma_f32_16x16x32_bf16 v[90:93], v[170:173], v[210:213], v[90:93]
	v_mfma_f32_16x16x32_bf16 v[82:85], v[162:165], v[218:221], v[82:85]
	v_mfma_f32_16x16x32_bf16 v[74:77], v[170:173], v[218:221], v[74:77]
	v_mfma_f32_16x16x32_bf16 v[118:121], v[174:177], v[190:193], v[118:121]
	v_mfma_f32_16x16x32_bf16 v[110:113], v[182:185], v[190:193], v[110:113]
	v_mfma_f32_16x16x32_bf16 v[102:105], v[174:177], v[198:201], v[102:105]
	v_mfma_f32_16x16x32_bf16 v[94:97], v[182:185], v[198:201], v[94:97]
	v_mfma_f32_16x16x32_bf16 v[86:89], v[174:177], v[206:209], v[86:89]
	v_mfma_f32_16x16x32_bf16 v[78:81], v[182:185], v[206:209], v[78:81]
	v_mfma_f32_16x16x32_bf16 v[70:73], v[174:177], v[214:217], v[70:73]
	v_mfma_f32_16x16x32_bf16 v[66:69], v[182:185], v[214:217], v[66:69]
	v_mfma_f32_16x16x32_bf16 v[118:121], v[178:181], v[194:197], v[118:121]
	v_mfma_f32_16x16x32_bf16 v[110:113], v[186:189], v[194:197], v[110:113]
	v_mfma_f32_16x16x32_bf16 v[102:105], v[178:181], v[202:205], v[102:105]
	v_mfma_f32_16x16x32_bf16 v[94:97], v[186:189], v[202:205], v[94:97]
	v_mfma_f32_16x16x32_bf16 v[86:89], v[178:181], v[210:213], v[86:89]
	v_mfma_f32_16x16x32_bf16 v[78:81], v[186:189], v[210:213], v[78:81]
	v_mfma_f32_16x16x32_bf16 v[70:73], v[178:181], v[218:221], v[70:73]
	v_mfma_f32_16x16x32_bf16 v[66:69], v[186:189], v[218:221], v[66:69]
	s_barrier
	s_add_i32 s24, s51, s27
	v_lshl_add_u64 v[154:155], v[154:155], 0, s[12:13]
	s_mov_b32 m0, s24
	ds_read_b128 v[190:193], v160 offset:49152
	ds_read_b128 v[194:197], v160 offset:50176
	ds_read_b128 v[198:201], v160 offset:51200
	ds_read_b128 v[202:205], v160 offset:52224
	ds_read_b128 v[206:209], v160 offset:53248
	ds_read_b128 v[210:213], v160 offset:54272
	ds_read_b128 v[214:217], v160 offset:55296
	ds_read_b128 v[218:221], v160 offset:56320
	global_load_lds_dwordx4 v[154:155], off
	s_add_i32 m0, s24, 0x2000
	s_add_u32 s22, s22, 0x180080
	v_lshl_add_u64 v[154:155], v[222:223], 0, s[12:13]
	s_addc_u32 s23, s23, 0
	s_add_i32 s24, s52, s27
	global_load_lds_dwordx4 v[154:155], off
	v_lshl_add_u64 v[154:155], s[22:23], 0, v[132:133]
	s_mov_b32 m0, s24
	s_nop 0
	global_load_lds_dwordx4 v[154:155], off
	v_lshl_add_u64 v[154:155], s[22:23], 0, v[136:137]
	s_add_i32 m0, s24, 0x2000
	s_nop 0
	global_load_lds_dwordx4 v[154:155], off
	v_lshl_add_u64 v[154:155], v[224:225], 0, s[12:13]
	s_mov_b32 m0, s36
	s_nop 0
	global_load_lds_dwordx4 v[154:155], off
	v_lshl_add_u64 v[154:155], v[226:227], 0, s[12:13]
	s_mov_b32 m0, s37
	s_nop 0
	global_load_lds_dwordx4 v[154:155], off
	s_waitcnt vmcnt(8)
	s_waitcnt lgkmcnt(0)
	s_barrier
	s_waitcnt lgkmcnt(0)
	v_mfma_f32_16x16x32_bf16 v[62:65], v[150:153], v[190:193], v[62:65]
	v_mfma_f32_16x16x32_bf16 v[58:61], v[166:169], v[190:193], v[58:61]
	v_mfma_f32_16x16x32_bf16 v[50:53], v[150:153], v[198:201], v[50:53]
	v_mfma_f32_16x16x32_bf16 v[42:45], v[166:169], v[198:201], v[42:45]
	v_mfma_f32_16x16x32_bf16 v[34:37], v[150:153], v[206:209], v[34:37]
	v_mfma_f32_16x16x32_bf16 v[26:29], v[166:169], v[206:209], v[26:29]
	v_mfma_f32_16x16x32_bf16 v[18:21], v[150:153], v[214:217], v[18:21]
	v_mfma_f32_16x16x32_bf16 v[10:13], v[166:169], v[214:217], v[10:13]
	v_mfma_f32_16x16x32_bf16 v[62:65], v[162:165], v[194:197], v[62:65]
	v_mfma_f32_16x16x32_bf16 v[58:61], v[170:173], v[194:197], v[58:61]
	v_mfma_f32_16x16x32_bf16 v[50:53], v[162:165], v[202:205], v[50:53]
	v_mfma_f32_16x16x32_bf16 v[42:45], v[170:173], v[202:205], v[42:45]
	v_mfma_f32_16x16x32_bf16 v[34:37], v[162:165], v[210:213], v[34:37]
	v_mfma_f32_16x16x32_bf16 v[26:29], v[170:173], v[210:213], v[26:29]
	v_mfma_f32_16x16x32_bf16 v[18:21], v[162:165], v[218:221], v[18:21]
	v_mfma_f32_16x16x32_bf16 v[10:13], v[170:173], v[218:221], v[10:13]
	v_mfma_f32_16x16x32_bf16 v[54:57], v[174:177], v[190:193], v[54:57]
	v_mfma_f32_16x16x32_bf16 v[46:49], v[182:185], v[190:193], v[46:49]
	v_mfma_f32_16x16x32_bf16 v[38:41], v[174:177], v[198:201], v[38:41]
	v_mfma_f32_16x16x32_bf16 v[30:33], v[182:185], v[198:201], v[30:33]
	v_mfma_f32_16x16x32_bf16 v[22:25], v[174:177], v[206:209], v[22:25]
	v_mfma_f32_16x16x32_bf16 v[14:17], v[182:185], v[206:209], v[14:17]
	v_mfma_f32_16x16x32_bf16 v[6:9], v[174:177], v[214:217], v[6:9]
	v_mfma_f32_16x16x32_bf16 v[2:5], v[182:185], v[214:217], v[2:5]
	v_mfma_f32_16x16x32_bf16 v[54:57], v[178:181], v[194:197], v[54:57]
	v_mfma_f32_16x16x32_bf16 v[46:49], v[186:189], v[194:197], v[46:49]
	v_mfma_f32_16x16x32_bf16 v[38:41], v[178:181], v[202:205], v[38:41]
	v_mfma_f32_16x16x32_bf16 v[30:33], v[186:189], v[202:205], v[30:33]
	v_mfma_f32_16x16x32_bf16 v[22:25], v[178:181], v[210:213], v[22:25]
	v_mfma_f32_16x16x32_bf16 v[14:17], v[186:189], v[210:213], v[14:17]
	v_mfma_f32_16x16x32_bf16 v[6:9], v[178:181], v[218:221], v[6:9]
	v_mfma_f32_16x16x32_bf16 v[2:5], v[186:189], v[218:221], v[2:5]
	s_barrier
	s_add_i32 s50, s50, 2
	s_add_u32 s20, s20, 0x100
	s_addc_u32 s21, s21, 0
	s_cmpk_gt_u32 s50, 0x5d
	s_cbranch_scc1 .LBB0_955

.LBB0_1033:
	ds_read_b128 v[140:143], v151
	ds_read_b128 v[144:147], v151 offset:1024
	ds_read_b128 v[154:157], v151 offset:2048
	ds_read_b128 v[158:161], v151 offset:3072
	ds_read_b128 v[162:165], v152
	ds_read_b128 v[166:169], v152 offset:1024
	ds_read_b128 v[170:173], v152 offset:2048
	ds_read_b128 v[174:177], v152 offset:3072
	s_add_u32 s36, s34, 0xfff80080
	s_addc_u32 s37, s35, -1
	s_cmp_eq_u32 s56, 28
	s_cselect_b32 s39, s25, s37
	s_cselect_b32 s38, s52, s36
	s_cselect_b32 s37, s23, s55
	s_cselect_b32 s36, s53, s54
	v_lshl_add_u64 v[210:211], s[34:35], 0, v[132:133]
	s_add_i32 m0, s31, 0xc000
	ds_read_b128 v[178:181], v153
	ds_read_b128 v[182:185], v153 offset:1024
	ds_read_b128 v[186:189], v153 offset:2048
	ds_read_b128 v[190:193], v153 offset:3072
	ds_read_b128 v[194:197], v153 offset:4096
	ds_read_b128 v[198:201], v153 offset:5120
	ds_read_b128 v[202:205], v153 offset:6144
	ds_read_b128 v[206:209], v153 offset:7168
	global_load_lds_dwordx4 v[210:211], off
	v_lshl_add_u64 v[210:211], s[34:35], 0, v[134:135]
	s_add_i32 m0, s31, 0xe000
	s_nop 0
	global_load_lds_dwordx4 v[210:211], off
	s_waitcnt vmcnt(8)
	s_waitcnt lgkmcnt(0)
	s_barrier
	s_waitcnt lgkmcnt(0)
	v_mfma_f32_16x16x32_bf16 v[124:127], v[140:143], v[178:181], v[124:127]
	v_mfma_f32_16x16x32_bf16 v[120:123], v[154:157], v[178:181], v[120:123]
	v_mfma_f32_16x16x32_bf16 v[112:115], v[140:143], v[186:189], v[112:115]
	v_mfma_f32_16x16x32_bf16 v[108:111], v[154:157], v[186:189], v[108:111]
	v_mfma_f32_16x16x32_bf16 v[96:99], v[140:143], v[194:197], v[96:99]
	v_mfma_f32_16x16x32_bf16 v[92:95], v[154:157], v[194:197], v[92:95]
	v_mfma_f32_16x16x32_bf16 v[80:83], v[140:143], v[202:205], v[80:83]
	v_mfma_f32_16x16x32_bf16 v[76:79], v[154:157], v[202:205], v[76:79]
	v_mfma_f32_16x16x32_bf16 v[124:127], v[144:147], v[182:185], v[124:127]
	v_mfma_f32_16x16x32_bf16 v[120:123], v[158:161], v[182:185], v[120:123]
	v_mfma_f32_16x16x32_bf16 v[112:115], v[144:147], v[190:193], v[112:115]
	v_mfma_f32_16x16x32_bf16 v[108:111], v[158:161], v[190:193], v[108:111]
	v_mfma_f32_16x16x32_bf16 v[96:99], v[144:147], v[198:201], v[96:99]
	v_mfma_f32_16x16x32_bf16 v[92:95], v[158:161], v[198:201], v[92:95]
	v_mfma_f32_16x16x32_bf16 v[80:83], v[144:147], v[206:209], v[80:83]
	v_mfma_f32_16x16x32_bf16 v[76:79], v[158:161], v[206:209], v[76:79]
	v_mfma_f32_16x16x32_bf16 v[116:119], v[162:165], v[178:181], v[116:119]
	v_mfma_f32_16x16x32_bf16 v[104:107], v[170:173], v[178:181], v[104:107]
	v_mfma_f32_16x16x32_bf16 v[100:103], v[162:165], v[186:189], v[100:103]
	v_mfma_f32_16x16x32_bf16 v[88:91], v[170:173], v[186:189], v[88:91]
	v_mfma_f32_16x16x32_bf16 v[84:87], v[162:165], v[194:197], v[84:87]
	v_mfma_f32_16x16x32_bf16 v[72:75], v[170:173], v[194:197], v[72:75]
	v_mfma_f32_16x16x32_bf16 v[68:71], v[162:165], v[202:205], v[68:71]
	v_mfma_f32_16x16x32_bf16 v[64:67], v[170:173], v[202:205], v[64:67]
	v_mfma_f32_16x16x32_bf16 v[116:119], v[166:169], v[182:185], v[116:119]
	v_mfma_f32_16x16x32_bf16 v[104:107], v[174:177], v[182:185], v[104:107]
	v_mfma_f32_16x16x32_bf16 v[100:103], v[166:169], v[190:193], v[100:103]
	v_mfma_f32_16x16x32_bf16 v[88:91], v[174:177], v[190:193], v[88:91]
	v_mfma_f32_16x16x32_bf16 v[84:87], v[166:169], v[198:201], v[84:87]
	v_mfma_f32_16x16x32_bf16 v[72:75], v[174:177], v[198:201], v[72:75]
	v_mfma_f32_16x16x32_bf16 v[68:71], v[166:169], v[206:209], v[68:71]
	v_mfma_f32_16x16x32_bf16 v[64:67], v[174:177], v[206:209], v[64:67]
	s_barrier
	s_add_i32 s57, s49, s40
	v_lshl_add_u64 v[210:211], s[36:37], 0, v[128:129]
	s_mov_b32 m0, s57
	ds_read_b128 v[178:181], v153 offset:16384
	ds_read_b128 v[182:185], v153 offset:17408
	ds_read_b128 v[186:189], v153 offset:18432
	ds_read_b128 v[190:193], v153 offset:19456
	ds_read_b128 v[194:197], v153 offset:20480
	ds_read_b128 v[198:201], v153 offset:21504
	ds_read_b128 v[202:205], v153 offset:22528
	ds_read_b128 v[206:209], v153 offset:23552
	global_load_lds_dwordx4 v[210:211], off
	s_add_i32 m0, s57, 0x2000
	s_add_u32 s58, s36, 0x80000
	v_lshl_add_u64 v[212:213], s[36:37], 0, v[130:131]
	s_addc_u32 s59, s37, 0
	s_add_i32 s57, s50, s40
	global_load_lds_dwordx4 v[212:213], off
	v_lshl_add_u64 v[214:215], s[58:59], 0, v[128:129]
	s_mov_b32 m0, s57
	v_lshl_add_u64 v[216:217], s[38:39], 0, v[130:131]
	global_load_lds_dwordx4 v[214:215], off
	v_lshl_add_u64 v[214:215], s[58:59], 0, v[130:131]
	s_add_i32 m0, s57, 0x2000
	s_nop 0
	global_load_lds_dwordx4 v[214:215], off
	v_lshl_add_u64 v[214:215], s[38:39], 0, v[128:129]
	s_mov_b32 m0, s31
	s_nop 0
	global_load_lds_dwordx4 v[214:215], off
	s_mov_b32 m0, s41
	s_nop 0
	global_load_lds_dwordx4 v[216:217], off
	s_waitcnt vmcnt(8)
	s_waitcnt lgkmcnt(0)
	s_barrier
	s_waitcnt lgkmcnt(0)
	v_mfma_f32_16x16x32_bf16 v[60:63], v[140:143], v[178:181], v[60:63]
	v_mfma_f32_16x16x32_bf16 v[56:59], v[154:157], v[178:181], v[56:59]
	v_mfma_f32_16x16x32_bf16 v[48:51], v[140:143], v[186:189], v[48:51]
	v_mfma_f32_16x16x32_bf16 v[44:47], v[154:157], v[186:189], v[44:47]
	v_mfma_f32_16x16x32_bf16 v[32:35], v[140:143], v[194:197], v[32:35]
	v_mfma_f32_16x16x32_bf16 v[28:31], v[154:157], v[194:197], v[28:31]
	v_mfma_f32_16x16x32_bf16 v[16:19], v[140:143], v[202:205], v[16:19]
	v_mfma_f32_16x16x32_bf16 v[12:15], v[154:157], v[202:205], v[12:15]
	v_mfma_f32_16x16x32_bf16 v[60:63], v[144:147], v[182:185], v[60:63]
	v_mfma_f32_16x16x32_bf16 v[56:59], v[158:161], v[182:185], v[56:59]
	v_mfma_f32_16x16x32_bf16 v[48:51], v[144:147], v[190:193], v[48:51]
	v_mfma_f32_16x16x32_bf16 v[44:47], v[158:161], v[190:193], v[44:47]
	v_mfma_f32_16x16x32_bf16 v[32:35], v[144:147], v[198:201], v[32:35]
	v_mfma_f32_16x16x32_bf16 v[28:31], v[158:161], v[198:201], v[28:31]
	v_mfma_f32_16x16x32_bf16 v[16:19], v[144:147], v[206:209], v[16:19]
	v_mfma_f32_16x16x32_bf16 v[12:15], v[158:161], v[206:209], v[12:15]
	v_mfma_f32_16x16x32_bf16 v[52:55], v[162:165], v[178:181], v[52:55]
	v_mfma_f32_16x16x32_bf16 v[40:43], v[170:173], v[178:181], v[40:43]
	v_mfma_f32_16x16x32_bf16 v[36:39], v[162:165], v[186:189], v[36:39]
	v_mfma_f32_16x16x32_bf16 v[24:27], v[170:173], v[186:189], v[24:27]
	v_mfma_f32_16x16x32_bf16 v[20:23], v[162:165], v[194:197], v[20:23]
	v_mfma_f32_16x16x32_bf16 v[8:11], v[170:173], v[194:197], v[8:11]
	v_mfma_f32_16x16x32_bf16 v[4:7], v[162:165], v[202:205], v[4:7]
	v_mfma_f32_16x16x32_bf16 v[0:3], v[170:173], v[202:205], v[0:3]
	v_mfma_f32_16x16x32_bf16 v[52:55], v[166:169], v[182:185], v[52:55]
	v_mfma_f32_16x16x32_bf16 v[40:43], v[174:177], v[182:185], v[40:43]
	v_mfma_f32_16x16x32_bf16 v[36:39], v[166:169], v[190:193], v[36:39]
	v_mfma_f32_16x16x32_bf16 v[24:27], v[174:177], v[190:193], v[24:27]
	v_mfma_f32_16x16x32_bf16 v[20:23], v[166:169], v[198:201], v[20:23]
	v_mfma_f32_16x16x32_bf16 v[8:11], v[174:177], v[198:201], v[8:11]
	v_mfma_f32_16x16x32_bf16 v[4:7], v[166:169], v[206:209], v[4:7]
	v_mfma_f32_16x16x32_bf16 v[0:3], v[174:177], v[206:209], v[0:3]
	s_barrier
	s_add_i32 s57, 0, 0x18000
	s_add_i32 s58, 0, 0x1c000
	v_add_u32_e32 v158, s57, v149
	v_add_u32_e32 v174, s58, v149
	ds_read_b128 v[140:143], v158
	ds_read_b128 v[144:147], v158 offset:1024
	ds_read_b128 v[154:157], v158 offset:2048
	ds_read_b128 v[158:161], v158 offset:3072
	ds_read_b128 v[162:165], v174
	ds_read_b128 v[166:169], v174 offset:1024
	ds_read_b128 v[170:173], v174 offset:2048
	ds_read_b128 v[174:177], v174 offset:3072
	s_add_u32 s38, s38, 0x80000
	s_addc_u32 s39, s39, 0
	s_mov_b32 m0, s42
	v_lshl_add_u64 v[218:219], s[38:39], 0, v[128:129]
	ds_read_b128 v[178:181], v153 offset:32768
	ds_read_b128 v[182:185], v153 offset:33792
	ds_read_b128 v[186:189], v153 offset:34816
	ds_read_b128 v[190:193], v153 offset:35840
	ds_read_b128 v[194:197], v153 offset:36864
	ds_read_b128 v[198:201], v153 offset:37888
	ds_read_b128 v[202:205], v153 offset:38912
	ds_read_b128 v[206:209], v153 offset:39936
	global_load_lds_dwordx4 v[218:219], off
	v_lshl_add_u64 v[218:219], s[38:39], 0, v[130:131]
	s_mov_b32 m0, s43
	s_nop 0
	global_load_lds_dwordx4 v[218:219], off
	s_waitcnt vmcnt(8)
	s_waitcnt lgkmcnt(0)
	s_barrier
	s_waitcnt lgkmcnt(0)
	v_mfma_f32_16x16x32_bf16 v[124:127], v[140:143], v[178:181], v[124:127]
	v_mfma_f32_16x16x32_bf16 v[120:123], v[154:157], v[178:181], v[120:123]
	v_mfma_f32_16x16x32_bf16 v[112:115], v[140:143], v[186:189], v[112:115]
	v_mfma_f32_16x16x32_bf16 v[108:111], v[154:157], v[186:189], v[108:111]
	v_mfma_f32_16x16x32_bf16 v[96:99], v[140:143], v[194:197], v[96:99]
	v_mfma_f32_16x16x32_bf16 v[92:95], v[154:157], v[194:197], v[92:95]
	v_mfma_f32_16x16x32_bf16 v[80:83], v[140:143], v[202:205], v[80:83]
	v_mfma_f32_16x16x32_bf16 v[76:79], v[154:157], v[202:205], v[76:79]
	v_mfma_f32_16x16x32_bf16 v[124:127], v[144:147], v[182:185], v[124:127]
	v_mfma_f32_16x16x32_bf16 v[120:123], v[158:161], v[182:185], v[120:123]
	v_mfma_f32_16x16x32_bf16 v[112:115], v[144:147], v[190:193], v[112:115]
	v_mfma_f32_16x16x32_bf16 v[108:111], v[158:161], v[190:193], v[108:111]
	v_mfma_f32_16x16x32_bf16 v[96:99], v[144:147], v[198:201], v[96:99]
	v_mfma_f32_16x16x32_bf16 v[92:95], v[158:161], v[198:201], v[92:95]
	v_mfma_f32_16x16x32_bf16 v[80:83], v[144:147], v[206:209], v[80:83]
	v_mfma_f32_16x16x32_bf16 v[76:79], v[158:161], v[206:209], v[76:79]
	v_mfma_f32_16x16x32_bf16 v[116:119], v[162:165], v[178:181], v[116:119]
	v_mfma_f32_16x16x32_bf16 v[104:107], v[170:173], v[178:181], v[104:107]
	v_mfma_f32_16x16x32_bf16 v[100:103], v[162:165], v[186:189], v[100:103]
	v_mfma_f32_16x16x32_bf16 v[88:91], v[170:173], v[186:189], v[88:91]
	v_mfma_f32_16x16x32_bf16 v[84:87], v[162:165], v[194:197], v[84:87]
	v_mfma_f32_16x16x32_bf16 v[72:75], v[170:173], v[194:197], v[72:75]
	v_mfma_f32_16x16x32_bf16 v[68:71], v[162:165], v[202:205], v[68:71]
	v_mfma_f32_16x16x32_bf16 v[64:67], v[170:173], v[202:205], v[64:67]
	v_mfma_f32_16x16x32_bf16 v[116:119], v[166:169], v[182:185], v[116:119]
	v_mfma_f32_16x16x32_bf16 v[104:107], v[174:177], v[182:185], v[104:107]
	v_mfma_f32_16x16x32_bf16 v[100:103], v[166:169], v[190:193], v[100:103]
	v_mfma_f32_16x16x32_bf16 v[88:91], v[174:177], v[190:193], v[88:91]
	v_mfma_f32_16x16x32_bf16 v[84:87], v[166:169], v[198:201], v[84:87]
	v_mfma_f32_16x16x32_bf16 v[72:75], v[174:177], v[198:201], v[72:75]
	v_mfma_f32_16x16x32_bf16 v[68:71], v[166:169], v[206:209], v[68:71]
	v_mfma_f32_16x16x32_bf16 v[64:67], v[174:177], v[206:209], v[64:67]
	s_barrier
	s_add_i32 s38, s57, s40
	v_lshl_add_u64 v[210:211], v[210:211], 0, s[4:5]
	s_mov_b32 m0, s38
	ds_read_b128 v[178:181], v153 offset:49152
	ds_read_b128 v[182:185], v153 offset:50176
	ds_read_b128 v[186:189], v153 offset:51200
	ds_read_b128 v[190:193], v153 offset:52224
	ds_read_b128 v[194:197], v153 offset:53248
	ds_read_b128 v[198:201], v153 offset:54272
	ds_read_b128 v[202:205], v153 offset:55296
	ds_read_b128 v[206:209], v153 offset:56320
	global_load_lds_dwordx4 v[210:211], off
	s_add_i32 m0, s38, 0x2000
	s_add_u32 s36, s36, 0x80080
	v_lshl_add_u64 v[210:211], v[212:213], 0, s[4:5]
	s_addc_u32 s37, s37, 0
	s_add_i32 s38, s58, s40
	global_load_lds_dwordx4 v[210:211], off
	v_lshl_add_u64 v[210:211], s[36:37], 0, v[128:129]
	s_mov_b32 m0, s38
	s_nop 0
	global_load_lds_dwordx4 v[210:211], off
	v_lshl_add_u64 v[210:211], s[36:37], 0, v[130:131]
	s_add_i32 m0, s38, 0x2000
	s_nop 0
	global_load_lds_dwordx4 v[210:211], off
	v_lshl_add_u64 v[210:211], v[214:215], 0, s[4:5]
	s_mov_b32 m0, s46
	s_nop 0
	global_load_lds_dwordx4 v[210:211], off
	v_lshl_add_u64 v[210:211], v[216:217], 0, s[4:5]
	s_mov_b32 m0, s47
	s_nop 0
	global_load_lds_dwordx4 v[210:211], off
	s_waitcnt vmcnt(8)
	s_waitcnt lgkmcnt(0)
	s_barrier
	s_waitcnt lgkmcnt(0)
	v_mfma_f32_16x16x32_bf16 v[60:63], v[140:143], v[178:181], v[60:63]
	v_mfma_f32_16x16x32_bf16 v[56:59], v[154:157], v[178:181], v[56:59]
	v_mfma_f32_16x16x32_bf16 v[48:51], v[140:143], v[186:189], v[48:51]
	v_mfma_f32_16x16x32_bf16 v[44:47], v[154:157], v[186:189], v[44:47]
	v_mfma_f32_16x16x32_bf16 v[32:35], v[140:143], v[194:197], v[32:35]
	v_mfma_f32_16x16x32_bf16 v[28:31], v[154:157], v[194:197], v[28:31]
	v_mfma_f32_16x16x32_bf16 v[16:19], v[140:143], v[202:205], v[16:19]
	v_mfma_f32_16x16x32_bf16 v[12:15], v[154:157], v[202:205], v[12:15]
	v_mfma_f32_16x16x32_bf16 v[60:63], v[144:147], v[182:185], v[60:63]
	v_mfma_f32_16x16x32_bf16 v[56:59], v[158:161], v[182:185], v[56:59]
	v_mfma_f32_16x16x32_bf16 v[48:51], v[144:147], v[190:193], v[48:51]
	v_mfma_f32_16x16x32_bf16 v[44:47], v[158:161], v[190:193], v[44:47]
	v_mfma_f32_16x16x32_bf16 v[32:35], v[144:147], v[198:201], v[32:35]
	v_mfma_f32_16x16x32_bf16 v[28:31], v[158:161], v[198:201], v[28:31]
	v_mfma_f32_16x16x32_bf16 v[16:19], v[144:147], v[206:209], v[16:19]
	v_mfma_f32_16x16x32_bf16 v[12:15], v[158:161], v[206:209], v[12:15]
	v_mfma_f32_16x16x32_bf16 v[52:55], v[162:165], v[178:181], v[52:55]
	v_mfma_f32_16x16x32_bf16 v[40:43], v[170:173], v[178:181], v[40:43]
	v_mfma_f32_16x16x32_bf16 v[36:39], v[162:165], v[186:189], v[36:39]
	v_mfma_f32_16x16x32_bf16 v[24:27], v[170:173], v[186:189], v[24:27]
	v_mfma_f32_16x16x32_bf16 v[20:23], v[162:165], v[194:197], v[20:23]
	v_mfma_f32_16x16x32_bf16 v[8:11], v[170:173], v[194:197], v[8:11]
	v_mfma_f32_16x16x32_bf16 v[4:7], v[162:165], v[202:205], v[4:7]
	v_mfma_f32_16x16x32_bf16 v[0:3], v[170:173], v[202:205], v[0:3]
	v_mfma_f32_16x16x32_bf16 v[52:55], v[166:169], v[182:185], v[52:55]
	v_mfma_f32_16x16x32_bf16 v[40:43], v[174:177], v[182:185], v[40:43]
	v_mfma_f32_16x16x32_bf16 v[36:39], v[166:169], v[190:193], v[36:39]
	v_mfma_f32_16x16x32_bf16 v[24:27], v[174:177], v[190:193], v[24:27]
	v_mfma_f32_16x16x32_bf16 v[20:23], v[166:169], v[198:201], v[20:23]
	v_mfma_f32_16x16x32_bf16 v[8:11], v[174:177], v[198:201], v[8:11]
	v_mfma_f32_16x16x32_bf16 v[4:7], v[166:169], v[206:209], v[4:7]
	v_mfma_f32_16x16x32_bf16 v[0:3], v[174:177], v[206:209], v[0:3]
	s_barrier
	s_add_i32 s56, s56, 2
	s_add_u32 s34, s34, 0x100
	s_addc_u32 s35, s35, 0
	s_add_u32 s54, s54, 0x100
	s_addc_u32 s55, s55, 0
	s_cmp_gt_u32 s56, 29
	s_cbranch_scc0 .LBB0_1033
	s_and_b64 vcc, exec, s[6:7]
	s_cbranch_vccz .LBB0_1036
	s_barrier
